# attention loop: counted lgkmcnt waits, dead negm copies removed, pad nops removed, rare path out of line, s_setprio 1 around MFMA segments
# baseline (speedup 1.0000x reference)
; #define AT_BAR() do { __builtin_amdgcn_sched_barrier(0); asm volatile("s_waitcnt lgkmcnt(0)\n\ts_barrier" ::: "memory"); __builtin_amdgcn_sched_barrier(0); } while (0)
; #define AT_PIN_M() asm volatile("" : "+v"(p[0]), "+v"(p[1]), "+v"(o[0][0]), "+v"(o[0][1]), "+v"(o[1][0]), "+v"(o[1][1]))
; __device__ __forceinline__ void attn_phase(LAS unsigned char* lds, const bf16_t* Qb, const bf16_t* Kimg, const bf16_t* Vimg, bf16_t* AB, int bid, int G, int wave_k) {
;     ...
;         for (int t = 0; t < 256; ++t) {
;             AT_MSEG(b_cur, 0, (t > 0 ? b_prev : b_cur), 2);
;             AT_PIN_M();
;             AT_BAR();
;             AT_SM(t == 0);
;             AT_BAR();
.LBB0_963:
	s_mov_b32 s64, s16
	v_add_u32_e32 v160, s62, v236
	v_add_u32_e32 v128, s64, v236
	ds_read_b128 v[104:107], v160
	ds_read_b128 v[108:111], v160 offset:2048
	ds_read_b128 v[120:123], v160 offset:4096
	ds_read_b128 v[124:127], v160 offset:6144
	ds_read_b128 v[210:213], v160 offset:8192
	ds_read_b128 v[230:233], v160 offset:10240
	ds_read_b128 v[238:241], v128 offset:16384
	ds_read_b128 v[242:245], v128 offset:16896
	ds_read_b128 v[246:249], v128 offset:18432
	ds_read_b128 v[250:253], v128 offset:18944
	s_setprio 1
	s_waitcnt lgkmcnt(9)
	v_mfma_f32_32x32x16_bf16 v[144:159], v[104:107], v[162:165], v[64:79]
	v_mfma_f32_32x32x16_bf16 v[128:143], v[104:107], v[186:189], v[80:95]
	s_waitcnt lgkmcnt(8)
	v_mfma_f32_32x32x16_bf16 v[144:159], v[108:111], v[166:169], v[144:159]
	v_mfma_f32_32x32x16_bf16 v[128:143], v[108:111], v[190:193], v[128:143]
	s_waitcnt lgkmcnt(7)
	v_mfma_f32_32x32x16_bf16 v[144:159], v[120:123], v[170:173], v[144:159]
	v_mfma_f32_32x32x16_bf16 v[128:143], v[120:123], v[194:197], v[128:143]
	s_waitcnt lgkmcnt(6)
	v_mfma_f32_32x32x16_bf16 v[144:159], v[124:127], v[174:177], v[144:159]
	v_mfma_f32_32x32x16_bf16 v[128:143], v[124:127], v[198:201], v[128:143]
	s_waitcnt lgkmcnt(5)
	v_mfma_f32_32x32x16_bf16 v[144:159], v[210:213], v[178:181], v[144:159]
	v_mfma_f32_32x32x16_bf16 v[128:143], v[210:213], v[202:205], v[128:143]
	s_waitcnt lgkmcnt(4)
	v_mfma_f32_32x32x16_bf16 v[144:159], v[230:233], v[182:185], v[144:159]
	v_mfma_f32_32x32x16_bf16 v[128:143], v[230:233], v[206:209], v[128:143]
	s_waitcnt lgkmcnt(0)
	v_mfma_f32_32x32x16_bf16 v[48:63], v[238:241], v[116:119], v[48:63]
	v_mfma_f32_32x32x16_bf16 v[32:47], v[242:245], v[116:119], v[32:47]
	v_mfma_f32_32x32x16_bf16 v[16:31], v[238:241], v[100:103], v[16:31]
	v_mfma_f32_32x32x16_bf16 v[0:15], v[242:245], v[100:103], v[0:15]
	v_mfma_f32_32x32x16_bf16 v[48:63], v[246:249], v[112:115], v[48:63]
	v_mfma_f32_32x32x16_bf16 v[32:47], v[250:253], v[112:115], v[32:47]
	v_mfma_f32_32x32x16_bf16 v[16:31], v[246:249], v[96:99], v[16:31]
	v_mfma_f32_32x32x16_bf16 v[0:15], v[250:253], v[96:99], v[0:15]
	s_setprio 0
	s_waitcnt lgkmcnt(0)
	s_barrier
	s_nop 3
	v_max3_f32 v96, v144, v145, v146
	v_max3_f32 v97, v147, v148, v149
	v_max3_f32 v98, v131, v132, v133
	v_max3_f32 v96, v96, v150, v151
	v_max3_f32 v97, v97, v152, v153
	v_max3_f32 v98, v98, v136, v137
	v_max3_f32 v96, v96, v154, v155
	v_max3_f32 v97, v97, v156, v157
	v_max3_f32 v98, v98, v140, v141
	v_max3_f32 v96, v96, v158, v159
	v_max_f32_e32 v97, v96, v97
	v_max3_f32 v96, v128, v129, v130
	v_max3_f32 v96, v96, v134, v135
	v_max3_f32 v96, v96, v138, v139
	v_max3_f32 v96, v96, v142, v143
	v_max_f32_e32 v96, v96, v98
	v_max_f32_e32 v98, v97, v96
	v_cmp_lt_i32_e32 vcc, s87, v98
	s_cbranch_vccnz .Lat_rare_a

; #define AT_VM(N) asm volatile("s_waitcnt vmcnt(" #N ")" ::: "memory")
; #define AT_PIN_M() asm volatile("" : "+v"(p[0]), "+v"(p[1]), "+v"(o[0][0]), "+v"(o[0][1]), "+v"(o[1][0]), "+v"(o[1][1]))
; __device__ __forceinline__ void attn_phase(LAS unsigned char* lds, const bf16_t* Qb, const bf16_t* Kimg, const bf16_t* Vimg, bf16_t* AB, int bid, int G, int wave_k) {
;     ...
;             const bool issued = (t + 2 < 256);
;             if (issued) AT_ISSUE(t + 2, b_prev);
;             AT_MSEG(b_cur, 1, b_cur, 0);
;             AT_PIN_M();
;             if (grpB) { if (issued) AT_VM(2); else AT_VM(0); }
.LBB0_969:
	ds_read_b128 v[136:139], v160 offset:512
	ds_read_b128 v[140:143], v160 offset:2560
	ds_read_b128 v[154:157], v160 offset:4608
	ds_read_b128 v[210:213], v160 offset:6656
	ds_read_b128 v[222:225], v160 offset:8704
	ds_read_b128 v[230:233], v160 offset:10752
	ds_read_b128 v[238:241], v160 offset:12288
	ds_read_b128 v[242:245], v160 offset:12800
	ds_read_b128 v[246:249], v160 offset:14336
	ds_read_b128 v[250:253], v160 offset:14848
	s_setprio 1
	s_waitcnt lgkmcnt(9)
	v_mfma_f32_32x32x16_bf16 v[112:127], v[136:139], v[162:165], v[64:79]
	v_mfma_f32_32x32x16_bf16 v[96:111], v[136:139], v[186:189], v[80:95]
	s_waitcnt lgkmcnt(8)
	v_mfma_f32_32x32x16_bf16 v[112:127], v[140:143], v[166:169], v[112:127]
	v_mfma_f32_32x32x16_bf16 v[96:111], v[140:143], v[190:193], v[96:111]
	s_waitcnt lgkmcnt(7)
	v_mfma_f32_32x32x16_bf16 v[112:127], v[154:157], v[170:173], v[112:127]
	v_mfma_f32_32x32x16_bf16 v[96:111], v[154:157], v[194:197], v[96:111]
	s_waitcnt lgkmcnt(6)
	v_mfma_f32_32x32x16_bf16 v[112:127], v[210:213], v[174:177], v[112:127]
	v_mfma_f32_32x32x16_bf16 v[96:111], v[210:213], v[198:201], v[96:111]
	s_waitcnt lgkmcnt(5)
	v_mfma_f32_32x32x16_bf16 v[112:127], v[222:225], v[178:181], v[112:127]
	v_mfma_f32_32x32x16_bf16 v[96:111], v[222:225], v[202:205], v[96:111]
	s_waitcnt lgkmcnt(4)
	v_mfma_f32_32x32x16_bf16 v[112:127], v[230:233], v[182:185], v[112:127]
	v_mfma_f32_32x32x16_bf16 v[96:111], v[230:233], v[206:209], v[96:111]
	s_waitcnt lgkmcnt(0)
	v_mfma_f32_32x32x16_bf16 v[48:63], v[238:241], v[148:151], v[48:63]
	s_and_b64 vcc, exec, s[44:45]
	v_mfma_f32_32x32x16_bf16 v[32:47], v[242:245], v[148:151], v[32:47]
	v_mfma_f32_32x32x16_bf16 v[16:31], v[238:241], v[132:135], v[16:31]
	v_mfma_f32_32x32x16_bf16 v[0:15], v[242:245], v[132:135], v[0:15]
	v_mfma_f32_32x32x16_bf16 v[48:63], v[246:249], v[144:147], v[48:63]
	v_mfma_f32_32x32x16_bf16 v[32:47], v[250:253], v[144:147], v[32:47]
	v_mfma_f32_32x32x16_bf16 v[16:31], v[246:249], v[128:131], v[16:31]
	v_mfma_f32_32x32x16_bf16 v[0:15], v[250:253], v[128:131], v[0:15]
	s_setprio 0
	s_cbranch_vccnz .LBB0_974
	s_mov_b64 s[16:17], -1
	s_and_b64 vcc, exec, s[24:25]
	s_cbranch_vccz .LBB0_972
	s_waitcnt vmcnt(0)
	s_mov_b64 s[16:17], 0
